# byte-phase pin: post-attention code (gMLP, out-proj, res, gate/up, down) shifted +4 bytes with never-executed pads, tail (res 2 and last seams) kept at its position
# speedup vs baseline: 1.0045x; 1.0045x over previous
; __global__ void __launch_bounds__(512, 2) mk_fwd(Args args) {
;     ...
;                 for (int p = vcu; p < 256; p += G) {
;                     const int xcd = p >> 5, c = p & 31;
;     ...
; #pragma unroll 1
;                     for (int i = 0; i < 4; ++i) { const int bh = 2 * xcd + (i >> 1), qb = (i & 1) ? c : 63 - c;
;                         attn_unit2(lds, Qb, Kb, VT, Y, args.in[11] + l * 128, lam, 1.0f - lam0, bh >> 2, bh & 3, qb, wid); }
.LBB0_288:
	s_branch .LBB0_248
	s_nop 0
	s_nop 0

; #define PG8_BAR __builtin_amdgcn_s_barrier()
; template <class Epi, class Sched, bool ALIGN_EPI = false, bool SP2 = false>
; __device__ __forceinline__ void gemm_phase(PG8_LAS unsigned char* lds, const Gemm g, const Sched& S, const Epi& E, int wid0) {
;     ...
;         if constexpr (!Epi::AFTER_DRAIN) { E(acc, cur, wr, wc, fr, fq); S.done(cur); }
;         if (!has_next) break;
; #pragma unroll
;         for (int a = 0; a < 2; ++a)
; #pragma unroll
;             for (int b = 0; b < 2; ++b)
; #pragma unroll
;                 for (int m = 0; m < 4; ++m)
; #pragma unroll
;                     for (int n = 0; n < 2; ++n) acc[a][b][m][n] = (f32x4){0.f, 0.f, 0.f, 0.f};
;         cur = nxt; cA = nA; cB = nB; ++ui;
;         if constexpr (ALIGN_EPI) { if (wr == 1) PG8_BAR; }
.LBB0_649:
	s_or_b64 exec, exec, s[78:79]
	s_and_b64 vcc, exec, s[40:41]
	s_mov_b64 s[40:41], -1
	s_cbranch_vccnz .LBB0_618
	s_andn2_b64 vcc, exec, s[0:1]
	s_cbranch_vccnz .LBB0_617
	s_barrier
	s_branch .LBB0_617
	s_nop 0
	s_nop 0
	s_nop 0
